# v7: GEMM K-loop MFMAs reordered so the two k-steps of each accumulator issue back to back (same per-accumulator order, bit-exact)
# speedup vs baseline: 1.0180x; 1.0089x over previous
; #define PG8_STAGE(bufoff, gbase, voff) do { _Pragma("unroll") for (int _i = 0; _i < 2; ++_i) \
;         __builtin_amdgcn_global_load_lds((const unsigned*)((const char*)(gbase) + (voff)[_i]), (LAS unsigned*)(lds + (bufoff) + ldsw + _i * 8192), 16, 0, 0); } while (0)
; #define PG8_LDA(dst, b, h) do { _Pragma("unroll") for (int m = 0; m < 4; ++m) _Pragma("unroll") for (int k = 0; k < 2; ++k) dst[m][k] = *(const LAS bf16x8*)(lds + PG8_SA(b, h) + aoff + m * 2048 + k * 1024); } while (0)
; #define PG8_LDB(dst, b, h) do { _Pragma("unroll") for (int n = 0; n < 2; ++n) _Pragma("unroll") for (int k = 0; k < 2; ++k) dst[n][k] = *(const LAS bf16x8*)(lds + PG8_SB(b, h) + boff + n * 2048 + k * 1024); } while (0)
; #define PG8_MMA(ai, bj, At, Bt) do { __builtin_amdgcn_s_setprio(3); _Pragma("unroll") for (int m = 0; m < 4; ++m) _Pragma("unroll") for (int n = 0; n < 2; ++n) _Pragma("unroll") for (int k = 0; k < 2; ++k) \
;         acc[ai][bj][m][n] = __builtin_amdgcn_mfma_f32_16x16x32_bf16(Bt[n][k], At[m][k], acc[ai][bj][m][n], 0, 0, 0); __builtin_amdgcn_s_setprio(0); } while (0)
; #define PG8_WAIT_V(n) asm volatile("s_waitcnt vmcnt(" #n ")" ::: "memory")
; #define PG8_WAIT_L(n) asm volatile("s_waitcnt lgkmcnt(" #n ")" ::: "memory")
; #define PG8_BAR __builtin_amdgcn_s_barrier()
; #define PG8_SCHED __builtin_amdgcn_sched_barrier(0)
; template <class Epi>
; __device__ __forceinline__ void gemm_phase(LAS unsigned char* lds, const Gemm g, const StaticOrder& S, const Epi& E, const int tid) {
;     ...
;             PG8_LDB(B0, 0, 0); PG8_LDB(B1, 0, 1); PG8_SCHED; PG8_LDA(At, 0, 0); PG8_STAGE(PG8_SA(1, 1), a1 + hstepA, voffA);
;             PG8_WAIT_V(8); PG8_WAIT_L(0); PG8_BAR; PG8_MMA(0, 0, At, B0); PG8_MMA(0, 1, At, B1); PG8_BAR; PG8_SCHED;
;             PG8_LDA(At, 0, 1); PG8_STAGE(PG8_SB(0, 0), b2, voffB); PG8_STAGE(PG8_SB(0, 1), b2 + hstepB, voffB); PG8_STAGE(PG8_SA(0, 0), a2, voffA);
;             PG8_WAIT_V(8); PG8_WAIT_L(0); PG8_BAR; PG8_MMA(1, 0, At, B0); PG8_MMA(1, 1, At, B1); PG8_BAR; PG8_SCHED;
.LBB0_264:
	s_add_u32 s30, s6, 0x100
	s_addc_u32 s31, s7, 0
	s_add_u32 s4, s20, 0x80
	s_addc_u32 s5, s21, 0
	s_mov_b32 s6, 0
	s_add_i32 s20, s6, 2
	s_add_u32 s21, s4, 0x80
	s_addc_u32 s7, s5, 0
	s_add_i32 s55, 0, 0x10000
	s_cmp_eq_u32 s48, s6
	s_cselect_b32 s7, s79, s7
	s_cselect_b32 s6, s78, s21
	s_cselect_b32 vcc_hi, s81, s31
	s_cselect_b32 vcc_lo, s80, s30
	s_add_i32 s21, 0, 0x14000
	v_add_u32_e32 v152, s55, v169
	v_add_u32_e32 v156, s21, v169
	ds_read_b128 v[140:143], v152
	ds_read_b128 v[144:147], v152 offset:1024
	ds_read_b128 v[148:151], v152 offset:2048
	ds_read_b128 v[152:155], v152 offset:3072
	ds_read_b128 v[172:175], v156
	ds_read_b128 v[180:183], v156 offset:1024
	ds_read_b128 v[184:187], v156 offset:2048
	ds_read_b128 v[194:197], v156 offset:3072
	v_lshl_add_u64 v[156:157], s[4:5], 0, v[138:139]
	s_add_i32 m0, s94, 0xc000
	ds_read_b128 v[198:201], v171
	ds_read_b128 v[202:205], v171 offset:1024
	ds_read_b128 v[206:209], v171 offset:2048
	ds_read_b128 v[210:213], v171 offset:3072
	ds_read_b128 v[214:217], v171 offset:4096
	ds_read_b128 v[218:221], v171 offset:5120
	ds_read_b128 v[222:225], v171 offset:6144
	ds_read_b128 v[226:229], v171 offset:7168
	global_load_lds_dwordx4 v[156:157], off
	v_lshl_add_u64 v[156:157], s[4:5], 0, v[136:137]
	s_add_i32 m0, s94, 0xe000
	s_nop 0
	global_load_lds_dwordx4 v[156:157], off
	s_waitcnt vmcnt(8)
	s_waitcnt lgkmcnt(0)
	s_barrier
	s_setprio 3
	s_waitcnt lgkmcnt(0)
	v_mfma_f32_16x16x32_bf16 v[124:127], v[140:143], v[198:201], 0
	v_mfma_f32_16x16x32_bf16 v[124:127], v[144:147], v[202:205], v[124:127]
	v_mfma_f32_16x16x32_bf16 v[120:123], v[148:151], v[198:201], 0
	v_mfma_f32_16x16x32_bf16 v[120:123], v[152:155], v[202:205], v[120:123]
	v_mfma_f32_16x16x32_bf16 v[116:119], v[140:143], v[206:209], 0
	v_mfma_f32_16x16x32_bf16 v[116:119], v[144:147], v[210:213], v[116:119]
	v_mfma_f32_16x16x32_bf16 v[108:111], v[148:151], v[206:209], 0
	v_mfma_f32_16x16x32_bf16 v[108:111], v[152:155], v[210:213], v[108:111]
	v_mfma_f32_16x16x32_bf16 v[100:103], v[140:143], v[214:217], 0
	v_mfma_f32_16x16x32_bf16 v[100:103], v[144:147], v[218:221], v[100:103]
	v_mfma_f32_16x16x32_bf16 v[92:95], v[148:151], v[214:217], 0
	v_mfma_f32_16x16x32_bf16 v[92:95], v[152:155], v[218:221], v[92:95]
	v_mfma_f32_16x16x32_bf16 v[84:87], v[140:143], v[222:225], 0
	v_mfma_f32_16x16x32_bf16 v[84:87], v[144:147], v[226:229], v[84:87]
	v_mfma_f32_16x16x32_bf16 v[76:79], v[148:151], v[222:225], 0
	v_mfma_f32_16x16x32_bf16 v[76:79], v[152:155], v[226:229], v[76:79]
	s_setprio 0
	s_setprio 3
	v_mfma_f32_16x16x32_bf16 v[112:115], v[172:175], v[198:201], 0
	v_mfma_f32_16x16x32_bf16 v[112:115], v[180:183], v[202:205], v[112:115]
	v_mfma_f32_16x16x32_bf16 v[104:107], v[184:187], v[198:201], 0
	v_mfma_f32_16x16x32_bf16 v[104:107], v[194:197], v[202:205], v[104:107]
	v_mfma_f32_16x16x32_bf16 v[96:99], v[172:175], v[206:209], 0
	v_mfma_f32_16x16x32_bf16 v[96:99], v[180:183], v[210:213], v[96:99]
	v_mfma_f32_16x16x32_bf16 v[88:91], v[184:187], v[206:209], 0
	v_mfma_f32_16x16x32_bf16 v[88:91], v[194:197], v[210:213], v[88:91]
	v_mfma_f32_16x16x32_bf16 v[80:83], v[172:175], v[214:217], 0
	v_mfma_f32_16x16x32_bf16 v[80:83], v[180:183], v[218:221], v[80:83]
	v_mfma_f32_16x16x32_bf16 v[72:75], v[184:187], v[214:217], 0
	v_mfma_f32_16x16x32_bf16 v[72:75], v[194:197], v[218:221], v[72:75]
	v_mfma_f32_16x16x32_bf16 v[68:71], v[172:175], v[222:225], 0
	v_mfma_f32_16x16x32_bf16 v[68:71], v[180:183], v[226:229], v[68:71]
	v_mfma_f32_16x16x32_bf16 v[64:67], v[184:187], v[222:225], 0
	v_mfma_f32_16x16x32_bf16 v[64:67], v[194:197], v[226:229], v[64:67]
	s_setprio 0
	s_barrier
	s_add_i32 s55, s55, s93
	v_lshl_add_u64 v[156:157], vcc, 0, v[130:131]
	s_mov_b32 m0, s55
	ds_read_b128 v[198:201], v171 offset:16384
	ds_read_b128 v[202:205], v171 offset:17408
	ds_read_b128 v[206:209], v171 offset:18432
	ds_read_b128 v[210:213], v171 offset:19456
	ds_read_b128 v[214:217], v171 offset:20480
	ds_read_b128 v[218:221], v171 offset:21504
	ds_read_b128 v[222:225], v171 offset:22528
	ds_read_b128 v[226:229], v171 offset:23552
	global_load_lds_dwordx4 v[156:157], off
	s_add_i32 m0, s55, 0x2000
	v_lshl_add_u64 v[190:191], vcc, 0, v[134:135]
	s_add_u32 vcc_lo, vcc_lo, s91
	s_addc_u32 vcc_hi, vcc_hi, 0
	s_add_i32 s21, s21, s93
	global_load_lds_dwordx4 v[190:191], off
	v_lshl_add_u64 v[240:241], vcc, 0, v[130:131]
	s_mov_b32 m0, s21
	v_lshl_add_u64 v[242:243], vcc, 0, v[134:135]
	global_load_lds_dwordx4 v[240:241], off
	s_add_i32 m0, s21, 0x2000
	v_lshl_add_u64 v[244:245], s[6:7], 0, v[128:129]
	global_load_lds_dwordx4 v[242:243], off
	s_mov_b32 m0, s94
	v_lshl_add_u64 v[246:247], s[6:7], 0, v[132:133]
	global_load_lds_dwordx4 v[244:245], off
	s_mov_b32 m0, s95
	s_nop 0
	global_load_lds_dwordx4 v[246:247], off
	s_waitcnt vmcnt(8)
	s_waitcnt lgkmcnt(0)
	s_barrier
; #define PG8_STAGE(bufoff, gbase, voff) do { _Pragma("unroll") for (int _i = 0; _i < 2; ++_i) \
;         __builtin_amdgcn_global_load_lds((const unsigned*)((const char*)(gbase) + (voff)[_i]), (LAS unsigned*)(lds + (bufoff) + ldsw + _i * 8192), 16, 0, 0); } while (0)
; #define PG8_LDA(dst, b, h) do { _Pragma("unroll") for (int m = 0; m < 4; ++m) _Pragma("unroll") for (int k = 0; k < 2; ++k) dst[m][k] = *(const LAS bf16x8*)(lds + PG8_SA(b, h) + aoff + m * 2048 + k * 1024); } while (0)
; #define PG8_LDB(dst, b, h) do { _Pragma("unroll") for (int n = 0; n < 2; ++n) _Pragma("unroll") for (int k = 0; k < 2; ++k) dst[n][k] = *(const LAS bf16x8*)(lds + PG8_SB(b, h) + boff + n * 2048 + k * 1024); } while (0)
; #define PG8_MMA(ai, bj, At, Bt) do { __builtin_amdgcn_s_setprio(3); _Pragma("unroll") for (int m = 0; m < 4; ++m) _Pragma("unroll") for (int n = 0; n < 2; ++n) _Pragma("unroll") for (int k = 0; k < 2; ++k) \
;         acc[ai][bj][m][n] = __builtin_amdgcn_mfma_f32_16x16x32_bf16(Bt[n][k], At[m][k], acc[ai][bj][m][n], 0, 0, 0); __builtin_amdgcn_s_setprio(0); } while (0)
; #define PG8_WAIT_V(n) asm volatile("s_waitcnt vmcnt(" #n ")" ::: "memory")
; #define PG8_WAIT_L(n) asm volatile("s_waitcnt lgkmcnt(" #n ")" ::: "memory")
; #define PG8_BAR __builtin_amdgcn_s_barrier()
; #define PG8_SCHED __builtin_amdgcn_sched_barrier(0)
; template <class Epi>
; __device__ __forceinline__ void gemm_phase(LAS unsigned char* lds, const Gemm g, const StaticOrder& S, const Epi& E, const int tid) {
;     ...
;             PG8_WAIT_V(8); PG8_WAIT_L(0); PG8_BAR; PG8_MMA(1, 0, At, B0); PG8_MMA(1, 1, At, B1); PG8_BAR; PG8_SCHED;
;             PG8_LDB(B0, 1, 0); PG8_LDB(B1, 1, 1); PG8_SCHED; PG8_LDA(At, 1, 0); PG8_STAGE(PG8_SA(0, 1), a2 + hstepA, voffA);
;             PG8_WAIT_V(8); PG8_WAIT_L(0); PG8_BAR; PG8_MMA(0, 0, At, B0); PG8_MMA(0, 1, At, B1); PG8_BAR; PG8_SCHED;
	s_setprio 3
	s_waitcnt lgkmcnt(0)
	v_mfma_f32_16x16x32_bf16 v[60:63], v[140:143], v[198:201], 0
	v_mfma_f32_16x16x32_bf16 v[60:63], v[144:147], v[202:205], v[60:63]
	v_mfma_f32_16x16x32_bf16 v[56:59], v[148:151], v[198:201], 0
	v_mfma_f32_16x16x32_bf16 v[56:59], v[152:155], v[202:205], v[56:59]
	v_mfma_f32_16x16x32_bf16 v[48:51], v[140:143], v[206:209], 0
	v_mfma_f32_16x16x32_bf16 v[48:51], v[144:147], v[210:213], v[48:51]
	v_mfma_f32_16x16x32_bf16 v[40:43], v[148:151], v[206:209], 0
	v_mfma_f32_16x16x32_bf16 v[40:43], v[152:155], v[210:213], v[40:43]
	v_mfma_f32_16x16x32_bf16 v[32:35], v[140:143], v[214:217], 0
	v_mfma_f32_16x16x32_bf16 v[32:35], v[144:147], v[218:221], v[32:35]
	v_mfma_f32_16x16x32_bf16 v[24:27], v[148:151], v[214:217], 0
	v_mfma_f32_16x16x32_bf16 v[24:27], v[152:155], v[218:221], v[24:27]
	v_mfma_f32_16x16x32_bf16 v[16:19], v[140:143], v[222:225], 0
	v_mfma_f32_16x16x32_bf16 v[16:19], v[144:147], v[226:229], v[16:19]
	v_mfma_f32_16x16x32_bf16 v[8:11], v[148:151], v[222:225], 0
	v_mfma_f32_16x16x32_bf16 v[8:11], v[152:155], v[226:229], v[8:11]
	s_setprio 0
	s_setprio 3
	v_mfma_f32_16x16x32_bf16 v[52:55], v[172:175], v[198:201], 0
	v_mfma_f32_16x16x32_bf16 v[52:55], v[180:183], v[202:205], v[52:55]
	v_mfma_f32_16x16x32_bf16 v[44:47], v[184:187], v[198:201], 0
	v_mfma_f32_16x16x32_bf16 v[44:47], v[194:197], v[202:205], v[44:47]
	v_mfma_f32_16x16x32_bf16 v[36:39], v[172:175], v[206:209], 0
	v_mfma_f32_16x16x32_bf16 v[36:39], v[180:183], v[210:213], v[36:39]
	v_mfma_f32_16x16x32_bf16 v[28:31], v[184:187], v[206:209], 0
	v_mfma_f32_16x16x32_bf16 v[28:31], v[194:197], v[210:213], v[28:31]
	v_mfma_f32_16x16x32_bf16 v[20:23], v[172:175], v[214:217], 0
	v_mfma_f32_16x16x32_bf16 v[20:23], v[180:183], v[218:221], v[20:23]
	v_mfma_f32_16x16x32_bf16 v[12:15], v[184:187], v[214:217], 0
	v_mfma_f32_16x16x32_bf16 v[12:15], v[194:197], v[218:221], v[12:15]
	v_mfma_f32_16x16x32_bf16 v[4:7], v[172:175], v[222:225], 0
	v_mfma_f32_16x16x32_bf16 v[4:7], v[180:183], v[226:229], v[4:7]
	v_mfma_f32_16x16x32_bf16 v[0:3], v[184:187], v[222:225], 0
	v_mfma_f32_16x16x32_bf16 v[0:3], v[194:197], v[226:229], v[0:3]
	s_setprio 0
	s_barrier
	s_add_i32 s21, 0, 0x18000
	s_add_i32 s55, 0, 0x1c000
	v_add_u32_e32 v152, s21, v169
	v_add_u32_e32 v176, s55, v169
	ds_read_b128 v[140:143], v152
	ds_read_b128 v[144:147], v152 offset:1024
	ds_read_b128 v[148:151], v152 offset:2048
	ds_read_b128 v[152:155], v152 offset:3072
	ds_read_b128 v[172:175], v176
	ds_read_b128 v[180:183], v176 offset:1024
	ds_read_b128 v[184:187], v176 offset:2048
	ds_read_b128 v[194:197], v176 offset:3072
	s_add_u32 s6, s6, s26
	s_addc_u32 s7, s7, 0
	s_mov_b32 m0, s96
	v_lshl_add_u64 v[252:253], s[6:7], 0, v[128:129]
	ds_read_b128 v[198:201], v171 offset:32768
	ds_read_b128 v[202:205], v171 offset:33792
	ds_read_b128 v[206:209], v171 offset:34816
	ds_read_b128 v[210:213], v171 offset:35840
	ds_read_b128 v[214:217], v171 offset:36864
	ds_read_b128 v[218:221], v171 offset:37888
	ds_read_b128 v[222:225], v171 offset:38912
	ds_read_b128 v[226:229], v171 offset:39936
	global_load_lds_dwordx4 v[252:253], off
	v_lshl_add_u64 v[252:253], s[6:7], 0, v[132:133]
	s_mov_b32 m0, s97
	s_nop 0
	global_load_lds_dwordx4 v[252:253], off
	s_waitcnt vmcnt(8)
	s_waitcnt lgkmcnt(0)
	s_barrier
	s_setprio 3
	s_waitcnt lgkmcnt(0)
	v_mfma_f32_16x16x32_bf16 v[124:127], v[140:143], v[198:201], v[124:127]
	v_mfma_f32_16x16x32_bf16 v[124:127], v[144:147], v[202:205], v[124:127]
	v_mfma_f32_16x16x32_bf16 v[120:123], v[148:151], v[198:201], v[120:123]
	v_mfma_f32_16x16x32_bf16 v[120:123], v[152:155], v[202:205], v[120:123]
	v_mfma_f32_16x16x32_bf16 v[116:119], v[140:143], v[206:209], v[116:119]
	v_mfma_f32_16x16x32_bf16 v[116:119], v[144:147], v[210:213], v[116:119]
	v_mfma_f32_16x16x32_bf16 v[108:111], v[148:151], v[206:209], v[108:111]
	v_mfma_f32_16x16x32_bf16 v[108:111], v[152:155], v[210:213], v[108:111]
	v_mfma_f32_16x16x32_bf16 v[100:103], v[140:143], v[214:217], v[100:103]
	v_mfma_f32_16x16x32_bf16 v[100:103], v[144:147], v[218:221], v[100:103]
	v_mfma_f32_16x16x32_bf16 v[92:95], v[148:151], v[214:217], v[92:95]
	v_mfma_f32_16x16x32_bf16 v[92:95], v[152:155], v[218:221], v[92:95]
	v_mfma_f32_16x16x32_bf16 v[84:87], v[140:143], v[222:225], v[84:87]
	v_mfma_f32_16x16x32_bf16 v[84:87], v[144:147], v[226:229], v[84:87]
	v_mfma_f32_16x16x32_bf16 v[76:79], v[148:151], v[222:225], v[76:79]
	v_mfma_f32_16x16x32_bf16 v[76:79], v[152:155], v[226:229], v[76:79]
	s_setprio 0
	s_setprio 3
	v_mfma_f32_16x16x32_bf16 v[112:115], v[172:175], v[198:201], v[112:115]
	v_mfma_f32_16x16x32_bf16 v[112:115], v[180:183], v[202:205], v[112:115]
	v_mfma_f32_16x16x32_bf16 v[104:107], v[184:187], v[198:201], v[104:107]
	v_mfma_f32_16x16x32_bf16 v[104:107], v[194:197], v[202:205], v[104:107]
	v_mfma_f32_16x16x32_bf16 v[96:99], v[172:175], v[206:209], v[96:99]
	v_mfma_f32_16x16x32_bf16 v[96:99], v[180:183], v[210:213], v[96:99]
	v_mfma_f32_16x16x32_bf16 v[88:91], v[184:187], v[206:209], v[88:91]
	v_mfma_f32_16x16x32_bf16 v[88:91], v[194:197], v[210:213], v[88:91]
	v_mfma_f32_16x16x32_bf16 v[80:83], v[172:175], v[214:217], v[80:83]
	v_mfma_f32_16x16x32_bf16 v[80:83], v[180:183], v[218:221], v[80:83]
	v_mfma_f32_16x16x32_bf16 v[72:75], v[184:187], v[214:217], v[72:75]
	v_mfma_f32_16x16x32_bf16 v[72:75], v[194:197], v[218:221], v[72:75]
	v_mfma_f32_16x16x32_bf16 v[68:71], v[172:175], v[222:225], v[68:71]
	v_mfma_f32_16x16x32_bf16 v[68:71], v[180:183], v[226:229], v[68:71]
	v_mfma_f32_16x16x32_bf16 v[64:67], v[184:187], v[222:225], v[64:67]
	v_mfma_f32_16x16x32_bf16 v[64:67], v[194:197], v[226:229], v[64:67]
	s_setprio 0
	s_barrier
; #define PG8_STAGE(bufoff, gbase, voff) do { _Pragma("unroll") for (int _i = 0; _i < 2; ++_i) \
;         __builtin_amdgcn_global_load_lds((const unsigned*)((const char*)(gbase) + (voff)[_i]), (LAS unsigned*)(lds + (bufoff) + ldsw + _i * 8192), 16, 0, 0); } while (0)
; #define PG8_LDA(dst, b, h) do { _Pragma("unroll") for (int m = 0; m < 4; ++m) _Pragma("unroll") for (int k = 0; k < 2; ++k) dst[m][k] = *(const LAS bf16x8*)(lds + PG8_SA(b, h) + aoff + m * 2048 + k * 1024); } while (0)
; #define PG8_LDB(dst, b, h) do { _Pragma("unroll") for (int n = 0; n < 2; ++n) _Pragma("unroll") for (int k = 0; k < 2; ++k) dst[n][k] = *(const LAS bf16x8*)(lds + PG8_SB(b, h) + boff + n * 2048 + k * 1024); } while (0)
; #define PG8_MMA(ai, bj, At, Bt) do { __builtin_amdgcn_s_setprio(3); _Pragma("unroll") for (int m = 0; m < 4; ++m) _Pragma("unroll") for (int n = 0; n < 2; ++n) _Pragma("unroll") for (int k = 0; k < 2; ++k) \
;         acc[ai][bj][m][n] = __builtin_amdgcn_mfma_f32_16x16x32_bf16(Bt[n][k], At[m][k], acc[ai][bj][m][n], 0, 0, 0); __builtin_amdgcn_s_setprio(0); } while (0)
; #define PG8_WAIT_V(n) asm volatile("s_waitcnt vmcnt(" #n ")" ::: "memory")
; #define PG8_WAIT_L(n) asm volatile("s_waitcnt lgkmcnt(" #n ")" ::: "memory")
; #define PG8_BAR __builtin_amdgcn_s_barrier()
; #define PG8_SCHED __builtin_amdgcn_sched_barrier(0)
; template <class Epi>
; __device__ __forceinline__ void gemm_phase(LAS unsigned char* lds, const Gemm g, const StaticOrder& S, const Epi& E, const int tid) {
;     ...
;             PG8_LDB(B0, 0, 0); PG8_LDB(B1, 0, 1); PG8_SCHED; PG8_LDA(At, 0, 0); PG8_STAGE(PG8_SA(1, 1), a1 + hstepA, voffA);
;     ...
;             PG8_LDA(At, 1, 1); PG8_STAGE(PG8_SB(1, 0), b3, voffB); PG8_STAGE(PG8_SB(1, 1), b3 + hstepB, voffB); PG8_STAGE(PG8_SA(1, 0), a3, voffA);
;             PG8_WAIT_V(8); PG8_WAIT_L(0); PG8_BAR; PG8_MMA(1, 0, At, B0); PG8_MMA(1, 1, At, B1); PG8_BAR; PG8_SCHED;
	s_add_i32 s6, s21, s93
	v_lshl_add_u64 v[156:157], v[156:157], 0, s[22:23]
	s_mov_b32 m0, s6
	ds_read_b128 v[198:201], v171 offset:49152
	ds_read_b128 v[202:205], v171 offset:50176
	ds_read_b128 v[206:209], v171 offset:51200
	ds_read_b128 v[210:213], v171 offset:52224
	ds_read_b128 v[214:217], v171 offset:53248
	ds_read_b128 v[218:221], v171 offset:54272
	ds_read_b128 v[222:225], v171 offset:55296
	ds_read_b128 v[226:229], v171 offset:56320
	global_load_lds_dwordx4 v[156:157], off
	v_lshl_add_u64 v[156:157], v[190:191], 0, s[22:23]
	s_add_i32 m0, s6, 0x2000
	s_add_i32 s6, s55, s93
	global_load_lds_dwordx4 v[156:157], off
	v_lshl_add_u64 v[156:157], v[240:241], 0, s[22:23]
	s_mov_b32 m0, s6
	s_nop 0
	global_load_lds_dwordx4 v[156:157], off
	v_lshl_add_u64 v[156:157], v[242:243], 0, s[22:23]
	s_add_i32 m0, s6, 0x2000
	s_nop 0
	global_load_lds_dwordx4 v[156:157], off
	v_lshl_add_u64 v[156:157], v[244:245], 0, s[22:23]
	s_mov_b32 m0, s98
	s_nop 0
	global_load_lds_dwordx4 v[156:157], off
	v_lshl_add_u64 v[156:157], v[246:247], 0, s[22:23]
	s_mov_b32 m0, s99
	s_nop 0
	global_load_lds_dwordx4 v[156:157], off
	s_waitcnt vmcnt(8)
	s_waitcnt lgkmcnt(0)
	s_barrier
	s_setprio 3
	s_waitcnt lgkmcnt(0)
	v_mfma_f32_16x16x32_bf16 v[60:63], v[140:143], v[198:201], v[60:63]
	v_mfma_f32_16x16x32_bf16 v[60:63], v[144:147], v[202:205], v[60:63]
	v_mfma_f32_16x16x32_bf16 v[56:59], v[148:151], v[198:201], v[56:59]
	v_mfma_f32_16x16x32_bf16 v[56:59], v[152:155], v[202:205], v[56:59]
	v_mfma_f32_16x16x32_bf16 v[48:51], v[140:143], v[206:209], v[48:51]
	v_mfma_f32_16x16x32_bf16 v[48:51], v[144:147], v[210:213], v[48:51]
	v_mfma_f32_16x16x32_bf16 v[40:43], v[148:151], v[206:209], v[40:43]
	v_mfma_f32_16x16x32_bf16 v[40:43], v[152:155], v[210:213], v[40:43]
	v_mfma_f32_16x16x32_bf16 v[32:35], v[140:143], v[214:217], v[32:35]
	v_mfma_f32_16x16x32_bf16 v[32:35], v[144:147], v[218:221], v[32:35]
	v_mfma_f32_16x16x32_bf16 v[24:27], v[148:151], v[214:217], v[24:27]
	v_mfma_f32_16x16x32_bf16 v[24:27], v[152:155], v[218:221], v[24:27]
	v_mfma_f32_16x16x32_bf16 v[16:19], v[140:143], v[222:225], v[16:19]
	v_mfma_f32_16x16x32_bf16 v[16:19], v[144:147], v[226:229], v[16:19]
	v_mfma_f32_16x16x32_bf16 v[8:11], v[148:151], v[222:225], v[8:11]
	v_mfma_f32_16x16x32_bf16 v[8:11], v[152:155], v[226:229], v[8:11]
	s_setprio 0
	s_setprio 3
	v_mfma_f32_16x16x32_bf16 v[52:55], v[172:175], v[198:201], v[52:55]
	v_mfma_f32_16x16x32_bf16 v[52:55], v[180:183], v[202:205], v[52:55]
	v_mfma_f32_16x16x32_bf16 v[44:47], v[184:187], v[198:201], v[44:47]
	v_mfma_f32_16x16x32_bf16 v[44:47], v[194:197], v[202:205], v[44:47]
	v_mfma_f32_16x16x32_bf16 v[36:39], v[172:175], v[206:209], v[36:39]
	v_mfma_f32_16x16x32_bf16 v[36:39], v[180:183], v[210:213], v[36:39]
	v_mfma_f32_16x16x32_bf16 v[28:31], v[184:187], v[206:209], v[28:31]
	v_mfma_f32_16x16x32_bf16 v[28:31], v[194:197], v[210:213], v[28:31]
	v_mfma_f32_16x16x32_bf16 v[20:23], v[172:175], v[214:217], v[20:23]
	v_mfma_f32_16x16x32_bf16 v[20:23], v[180:183], v[218:221], v[20:23]
	v_mfma_f32_16x16x32_bf16 v[12:15], v[184:187], v[214:217], v[12:15]
	v_mfma_f32_16x16x32_bf16 v[12:15], v[194:197], v[218:221], v[12:15]
	v_mfma_f32_16x16x32_bf16 v[4:7], v[172:175], v[222:225], v[4:7]
	v_mfma_f32_16x16x32_bf16 v[4:7], v[180:183], v[226:229], v[4:7]
	v_mfma_f32_16x16x32_bf16 v[0:3], v[184:187], v[222:225], v[0:3]
	v_mfma_f32_16x16x32_bf16 v[0:3], v[194:197], v[226:229], v[0:3]
	s_setprio 0
	s_barrier
	s_add_u32 s30, s30, 0x100
	s_addc_u32 s31, s31, 0
	s_add_u32 s4, s4, 0x100
	s_addc_u32 s5, s5, 0
	s_cmp_ge_u32 s20, s89
	s_mov_b32 s6, s20
	s_cbranch_scc1 .Lpg_kloop_done
.LBB0_265:
	s_add_i32 s20, s6, 2
	s_add_u32 s21, s4, 0x80
	s_addc_u32 s7, s5, 0
	s_add_i32 s55, 0, 0x10000
	s_cmp_eq_u32 s48, s6
	s_cselect_b32 s7, s79, s7
	s_cselect_b32 s6, s78, s21
	s_cselect_b32 vcc_hi, s81, s31
	s_cselect_b32 vcc_lo, s80, s30
	s_add_i32 s21, 0, 0x14000
	v_add_u32_e32 v152, s55, v169
	v_add_u32_e32 v156, s21, v169
	ds_read_b128 v[140:143], v152
	ds_read_b128 v[144:147], v152 offset:1024
	ds_read_b128 v[148:151], v152 offset:2048
	ds_read_b128 v[152:155], v152 offset:3072
	ds_read_b128 v[172:175], v156
	ds_read_b128 v[180:183], v156 offset:1024
	ds_read_b128 v[184:187], v156 offset:2048
	ds_read_b128 v[194:197], v156 offset:3072
	v_lshl_add_u64 v[156:157], s[4:5], 0, v[138:139]
	s_add_i32 m0, s94, 0xc000
	ds_read_b128 v[198:201], v171
	ds_read_b128 v[202:205], v171 offset:1024
	ds_read_b128 v[206:209], v171 offset:2048
	ds_read_b128 v[210:213], v171 offset:3072
	ds_read_b128 v[214:217], v171 offset:4096
	ds_read_b128 v[218:221], v171 offset:5120
	ds_read_b128 v[222:225], v171 offset:6144
	ds_read_b128 v[226:229], v171 offset:7168
	global_load_lds_dwordx4 v[156:157], off
	v_lshl_add_u64 v[156:157], s[4:5], 0, v[136:137]
	s_add_i32 m0, s94, 0xe000
	s_nop 0
	global_load_lds_dwordx4 v[156:157], off
	s_waitcnt vmcnt(8)
	s_waitcnt lgkmcnt(0)
	s_barrier
; #define PG8_STAGE(bufoff, gbase, voff) do { _Pragma("unroll") for (int _i = 0; _i < 2; ++_i) \
;         __builtin_amdgcn_global_load_lds((const unsigned*)((const char*)(gbase) + (voff)[_i]), (LAS unsigned*)(lds + (bufoff) + ldsw + _i * 8192), 16, 0, 0); } while (0)
; #define PG8_LDA(dst, b, h) do { _Pragma("unroll") for (int m = 0; m < 4; ++m) _Pragma("unroll") for (int k = 0; k < 2; ++k) dst[m][k] = *(const LAS bf16x8*)(lds + PG8_SA(b, h) + aoff + m * 2048 + k * 1024); } while (0)
; #define PG8_LDB(dst, b, h) do { _Pragma("unroll") for (int n = 0; n < 2; ++n) _Pragma("unroll") for (int k = 0; k < 2; ++k) dst[n][k] = *(const LAS bf16x8*)(lds + PG8_SB(b, h) + boff + n * 2048 + k * 1024); } while (0)
; #define PG8_MMA(ai, bj, At, Bt) do { __builtin_amdgcn_s_setprio(3); _Pragma("unroll") for (int m = 0; m < 4; ++m) _Pragma("unroll") for (int n = 0; n < 2; ++n) _Pragma("unroll") for (int k = 0; k < 2; ++k) \
;         acc[ai][bj][m][n] = __builtin_amdgcn_mfma_f32_16x16x32_bf16(Bt[n][k], At[m][k], acc[ai][bj][m][n], 0, 0, 0); __builtin_amdgcn_s_setprio(0); } while (0)
; #define PG8_WAIT_V(n) asm volatile("s_waitcnt vmcnt(" #n ")" ::: "memory")
; #define PG8_WAIT_L(n) asm volatile("s_waitcnt lgkmcnt(" #n ")" ::: "memory")
; #define PG8_BAR __builtin_amdgcn_s_barrier()
; #define PG8_SCHED __builtin_amdgcn_sched_barrier(0)
; template <class Epi>
; __device__ __forceinline__ void gemm_phase(LAS unsigned char* lds, const Gemm g, const StaticOrder& S, const Epi& E, const int tid) {
;     ...
;             PG8_LDB(B0, 0, 0); PG8_LDB(B1, 0, 1); PG8_SCHED; PG8_LDA(At, 0, 0); PG8_STAGE(PG8_SA(1, 1), a1 + hstepA, voffA);
;             PG8_WAIT_V(8); PG8_WAIT_L(0); PG8_BAR; PG8_MMA(0, 0, At, B0); PG8_MMA(0, 1, At, B1); PG8_BAR; PG8_SCHED;
;             PG8_LDA(At, 0, 1); PG8_STAGE(PG8_SB(0, 0), b2, voffB); PG8_STAGE(PG8_SB(0, 1), b2 + hstepB, voffB); PG8_STAGE(PG8_SA(0, 0), a2, voffA);
;             PG8_WAIT_V(8); PG8_WAIT_L(0); PG8_BAR; PG8_MMA(1, 0, At, B0); PG8_MMA(1, 1, At, B1); PG8_BAR; PG8_SCHED;
;             PG8_LDB(B0, 1, 0); PG8_LDB(B1, 1, 1); PG8_SCHED; PG8_LDA(At, 1, 0); PG8_STAGE(PG8_SA(0, 1), a2 + hstepA, voffA);
;             PG8_WAIT_V(8); PG8_WAIT_L(0); PG8_BAR; PG8_MMA(0, 0, At, B0); PG8_MMA(0, 1, At, B1); PG8_BAR; PG8_SCHED;
	s_setprio 3
	s_waitcnt lgkmcnt(0)
	v_mfma_f32_16x16x32_bf16 v[124:127], v[140:143], v[198:201], v[124:127]
	v_mfma_f32_16x16x32_bf16 v[124:127], v[144:147], v[202:205], v[124:127]
	v_mfma_f32_16x16x32_bf16 v[120:123], v[148:151], v[198:201], v[120:123]
	v_mfma_f32_16x16x32_bf16 v[120:123], v[152:155], v[202:205], v[120:123]
	v_mfma_f32_16x16x32_bf16 v[116:119], v[140:143], v[206:209], v[116:119]
	v_mfma_f32_16x16x32_bf16 v[116:119], v[144:147], v[210:213], v[116:119]
	v_mfma_f32_16x16x32_bf16 v[108:111], v[148:151], v[206:209], v[108:111]
	v_mfma_f32_16x16x32_bf16 v[108:111], v[152:155], v[210:213], v[108:111]
	v_mfma_f32_16x16x32_bf16 v[100:103], v[140:143], v[214:217], v[100:103]
	v_mfma_f32_16x16x32_bf16 v[100:103], v[144:147], v[218:221], v[100:103]
	v_mfma_f32_16x16x32_bf16 v[92:95], v[148:151], v[214:217], v[92:95]
	v_mfma_f32_16x16x32_bf16 v[92:95], v[152:155], v[218:221], v[92:95]
	v_mfma_f32_16x16x32_bf16 v[84:87], v[140:143], v[222:225], v[84:87]
	v_mfma_f32_16x16x32_bf16 v[84:87], v[144:147], v[226:229], v[84:87]
	v_mfma_f32_16x16x32_bf16 v[76:79], v[148:151], v[222:225], v[76:79]
	v_mfma_f32_16x16x32_bf16 v[76:79], v[152:155], v[226:229], v[76:79]
	s_setprio 0
	s_setprio 3
	v_mfma_f32_16x16x32_bf16 v[112:115], v[172:175], v[198:201], v[112:115]
	v_mfma_f32_16x16x32_bf16 v[112:115], v[180:183], v[202:205], v[112:115]
	v_mfma_f32_16x16x32_bf16 v[104:107], v[184:187], v[198:201], v[104:107]
	v_mfma_f32_16x16x32_bf16 v[104:107], v[194:197], v[202:205], v[104:107]
	v_mfma_f32_16x16x32_bf16 v[96:99], v[172:175], v[206:209], v[96:99]
	v_mfma_f32_16x16x32_bf16 v[96:99], v[180:183], v[210:213], v[96:99]
	v_mfma_f32_16x16x32_bf16 v[88:91], v[184:187], v[206:209], v[88:91]
	v_mfma_f32_16x16x32_bf16 v[88:91], v[194:197], v[210:213], v[88:91]
	v_mfma_f32_16x16x32_bf16 v[80:83], v[172:175], v[214:217], v[80:83]
	v_mfma_f32_16x16x32_bf16 v[80:83], v[180:183], v[218:221], v[80:83]
	v_mfma_f32_16x16x32_bf16 v[72:75], v[184:187], v[214:217], v[72:75]
	v_mfma_f32_16x16x32_bf16 v[72:75], v[194:197], v[218:221], v[72:75]
	v_mfma_f32_16x16x32_bf16 v[68:71], v[172:175], v[222:225], v[68:71]
	v_mfma_f32_16x16x32_bf16 v[68:71], v[180:183], v[226:229], v[68:71]
	v_mfma_f32_16x16x32_bf16 v[64:67], v[184:187], v[222:225], v[64:67]
	v_mfma_f32_16x16x32_bf16 v[64:67], v[194:197], v[226:229], v[64:67]
	s_setprio 0
	s_barrier
	s_add_i32 s55, s55, s93
	v_lshl_add_u64 v[156:157], vcc, 0, v[130:131]
	s_mov_b32 m0, s55
	ds_read_b128 v[198:201], v171 offset:16384
	ds_read_b128 v[202:205], v171 offset:17408
	ds_read_b128 v[206:209], v171 offset:18432
	ds_read_b128 v[210:213], v171 offset:19456
	ds_read_b128 v[214:217], v171 offset:20480
	ds_read_b128 v[218:221], v171 offset:21504
	ds_read_b128 v[222:225], v171 offset:22528
	ds_read_b128 v[226:229], v171 offset:23552
	global_load_lds_dwordx4 v[156:157], off
	s_add_i32 m0, s55, 0x2000
	v_lshl_add_u64 v[190:191], vcc, 0, v[134:135]
	s_add_u32 vcc_lo, vcc_lo, s91
	s_addc_u32 vcc_hi, vcc_hi, 0
	s_add_i32 s21, s21, s93
	global_load_lds_dwordx4 v[190:191], off
	v_lshl_add_u64 v[240:241], vcc, 0, v[130:131]
	s_mov_b32 m0, s21
	v_lshl_add_u64 v[242:243], vcc, 0, v[134:135]
	global_load_lds_dwordx4 v[240:241], off
	s_add_i32 m0, s21, 0x2000
	v_lshl_add_u64 v[244:245], s[6:7], 0, v[128:129]
	global_load_lds_dwordx4 v[242:243], off
	s_mov_b32 m0, s94
	v_lshl_add_u64 v[246:247], s[6:7], 0, v[132:133]
	global_load_lds_dwordx4 v[244:245], off
	s_mov_b32 m0, s95
	s_nop 0
	global_load_lds_dwordx4 v[246:247], off
	s_waitcnt vmcnt(8)
	s_waitcnt lgkmcnt(0)
	s_barrier
	s_setprio 3
	s_waitcnt lgkmcnt(0)
	v_mfma_f32_16x16x32_bf16 v[60:63], v[140:143], v[198:201], v[60:63]
	v_mfma_f32_16x16x32_bf16 v[60:63], v[144:147], v[202:205], v[60:63]
	v_mfma_f32_16x16x32_bf16 v[56:59], v[148:151], v[198:201], v[56:59]
	v_mfma_f32_16x16x32_bf16 v[56:59], v[152:155], v[202:205], v[56:59]
	v_mfma_f32_16x16x32_bf16 v[48:51], v[140:143], v[206:209], v[48:51]
	v_mfma_f32_16x16x32_bf16 v[48:51], v[144:147], v[210:213], v[48:51]
	v_mfma_f32_16x16x32_bf16 v[40:43], v[148:151], v[206:209], v[40:43]
	v_mfma_f32_16x16x32_bf16 v[40:43], v[152:155], v[210:213], v[40:43]
	v_mfma_f32_16x16x32_bf16 v[32:35], v[140:143], v[214:217], v[32:35]
	v_mfma_f32_16x16x32_bf16 v[32:35], v[144:147], v[218:221], v[32:35]
	v_mfma_f32_16x16x32_bf16 v[24:27], v[148:151], v[214:217], v[24:27]
	v_mfma_f32_16x16x32_bf16 v[24:27], v[152:155], v[218:221], v[24:27]
	v_mfma_f32_16x16x32_bf16 v[16:19], v[140:143], v[222:225], v[16:19]
	v_mfma_f32_16x16x32_bf16 v[16:19], v[144:147], v[226:229], v[16:19]
	v_mfma_f32_16x16x32_bf16 v[8:11], v[148:151], v[222:225], v[8:11]
	v_mfma_f32_16x16x32_bf16 v[8:11], v[152:155], v[226:229], v[8:11]
	s_setprio 0
	s_setprio 3
	v_mfma_f32_16x16x32_bf16 v[52:55], v[172:175], v[198:201], v[52:55]
	v_mfma_f32_16x16x32_bf16 v[52:55], v[180:183], v[202:205], v[52:55]
	v_mfma_f32_16x16x32_bf16 v[44:47], v[184:187], v[198:201], v[44:47]
	v_mfma_f32_16x16x32_bf16 v[44:47], v[194:197], v[202:205], v[44:47]
	v_mfma_f32_16x16x32_bf16 v[36:39], v[172:175], v[206:209], v[36:39]
	v_mfma_f32_16x16x32_bf16 v[36:39], v[180:183], v[210:213], v[36:39]
	v_mfma_f32_16x16x32_bf16 v[28:31], v[184:187], v[206:209], v[28:31]
	v_mfma_f32_16x16x32_bf16 v[28:31], v[194:197], v[210:213], v[28:31]
	v_mfma_f32_16x16x32_bf16 v[20:23], v[172:175], v[214:217], v[20:23]
	v_mfma_f32_16x16x32_bf16 v[20:23], v[180:183], v[218:221], v[20:23]
	v_mfma_f32_16x16x32_bf16 v[12:15], v[184:187], v[214:217], v[12:15]
	v_mfma_f32_16x16x32_bf16 v[12:15], v[194:197], v[218:221], v[12:15]
	v_mfma_f32_16x16x32_bf16 v[4:7], v[172:175], v[222:225], v[4:7]
	v_mfma_f32_16x16x32_bf16 v[4:7], v[180:183], v[226:229], v[4:7]
	v_mfma_f32_16x16x32_bf16 v[0:3], v[184:187], v[222:225], v[0:3]
	v_mfma_f32_16x16x32_bf16 v[0:3], v[194:197], v[226:229], v[0:3]
	s_setprio 0
	s_barrier
; #define PG8_STAGE(bufoff, gbase, voff) do { _Pragma("unroll") for (int _i = 0; _i < 2; ++_i) \
;         __builtin_amdgcn_global_load_lds((const unsigned*)((const char*)(gbase) + (voff)[_i]), (LAS unsigned*)(lds + (bufoff) + ldsw + _i * 8192), 16, 0, 0); } while (0)
; #define PG8_LDA(dst, b, h) do { _Pragma("unroll") for (int m = 0; m < 4; ++m) _Pragma("unroll") for (int k = 0; k < 2; ++k) dst[m][k] = *(const LAS bf16x8*)(lds + PG8_SA(b, h) + aoff + m * 2048 + k * 1024); } while (0)
; #define PG8_LDB(dst, b, h) do { _Pragma("unroll") for (int n = 0; n < 2; ++n) _Pragma("unroll") for (int k = 0; k < 2; ++k) dst[n][k] = *(const LAS bf16x8*)(lds + PG8_SB(b, h) + boff + n * 2048 + k * 1024); } while (0)
; #define PG8_MMA(ai, bj, At, Bt) do { __builtin_amdgcn_s_setprio(3); _Pragma("unroll") for (int m = 0; m < 4; ++m) _Pragma("unroll") for (int n = 0; n < 2; ++n) _Pragma("unroll") for (int k = 0; k < 2; ++k) \
;         acc[ai][bj][m][n] = __builtin_amdgcn_mfma_f32_16x16x32_bf16(Bt[n][k], At[m][k], acc[ai][bj][m][n], 0, 0, 0); __builtin_amdgcn_s_setprio(0); } while (0)
; #define PG8_WAIT_V(n) asm volatile("s_waitcnt vmcnt(" #n ")" ::: "memory")
; #define PG8_WAIT_L(n) asm volatile("s_waitcnt lgkmcnt(" #n ")" ::: "memory")
; #define PG8_BAR __builtin_amdgcn_s_barrier()
; #define PG8_SCHED __builtin_amdgcn_sched_barrier(0)
; template <class Epi>
; __device__ __forceinline__ void gemm_phase(LAS unsigned char* lds, const Gemm g, const StaticOrder& S, const Epi& E, const int tid) {
;     ...
;             PG8_LDB(B0, 1, 0); PG8_LDB(B1, 1, 1); PG8_SCHED; PG8_LDA(At, 1, 0); PG8_STAGE(PG8_SA(0, 1), a2 + hstepA, voffA);
;             PG8_WAIT_V(8); PG8_WAIT_L(0); PG8_BAR; PG8_MMA(0, 0, At, B0); PG8_MMA(0, 1, At, B1); PG8_BAR; PG8_SCHED;
	s_add_i32 s21, 0, 0x18000
	s_add_i32 s55, 0, 0x1c000
	v_add_u32_e32 v152, s21, v169
	v_add_u32_e32 v176, s55, v169
	ds_read_b128 v[140:143], v152
	ds_read_b128 v[144:147], v152 offset:1024
	ds_read_b128 v[148:151], v152 offset:2048
	ds_read_b128 v[152:155], v152 offset:3072
	ds_read_b128 v[172:175], v176
	ds_read_b128 v[180:183], v176 offset:1024
	ds_read_b128 v[184:187], v176 offset:2048
	ds_read_b128 v[194:197], v176 offset:3072
	s_add_u32 s6, s6, s26
	s_addc_u32 s7, s7, 0
	s_mov_b32 m0, s96
	v_lshl_add_u64 v[252:253], s[6:7], 0, v[128:129]
	ds_read_b128 v[198:201], v171 offset:32768
	ds_read_b128 v[202:205], v171 offset:33792
	ds_read_b128 v[206:209], v171 offset:34816
	ds_read_b128 v[210:213], v171 offset:35840
	ds_read_b128 v[214:217], v171 offset:36864
	ds_read_b128 v[218:221], v171 offset:37888
	ds_read_b128 v[222:225], v171 offset:38912
	ds_read_b128 v[226:229], v171 offset:39936
	global_load_lds_dwordx4 v[252:253], off
	v_lshl_add_u64 v[252:253], s[6:7], 0, v[132:133]
	s_mov_b32 m0, s97
	s_nop 0
	global_load_lds_dwordx4 v[252:253], off
	s_waitcnt vmcnt(8)
	s_waitcnt lgkmcnt(0)
	s_barrier
	s_setprio 3
	s_waitcnt lgkmcnt(0)
	v_mfma_f32_16x16x32_bf16 v[124:127], v[140:143], v[198:201], v[124:127]
	v_mfma_f32_16x16x32_bf16 v[124:127], v[144:147], v[202:205], v[124:127]
	v_mfma_f32_16x16x32_bf16 v[120:123], v[148:151], v[198:201], v[120:123]
	v_mfma_f32_16x16x32_bf16 v[120:123], v[152:155], v[202:205], v[120:123]
	v_mfma_f32_16x16x32_bf16 v[116:119], v[140:143], v[206:209], v[116:119]
	v_mfma_f32_16x16x32_bf16 v[116:119], v[144:147], v[210:213], v[116:119]
	v_mfma_f32_16x16x32_bf16 v[108:111], v[148:151], v[206:209], v[108:111]
	v_mfma_f32_16x16x32_bf16 v[108:111], v[152:155], v[210:213], v[108:111]
	v_mfma_f32_16x16x32_bf16 v[100:103], v[140:143], v[214:217], v[100:103]
	v_mfma_f32_16x16x32_bf16 v[100:103], v[144:147], v[218:221], v[100:103]
	v_mfma_f32_16x16x32_bf16 v[92:95], v[148:151], v[214:217], v[92:95]
	v_mfma_f32_16x16x32_bf16 v[92:95], v[152:155], v[218:221], v[92:95]
	v_mfma_f32_16x16x32_bf16 v[84:87], v[140:143], v[222:225], v[84:87]
	v_mfma_f32_16x16x32_bf16 v[84:87], v[144:147], v[226:229], v[84:87]
	v_mfma_f32_16x16x32_bf16 v[76:79], v[148:151], v[222:225], v[76:79]
	v_mfma_f32_16x16x32_bf16 v[76:79], v[152:155], v[226:229], v[76:79]
	s_setprio 0
	s_setprio 3
	v_mfma_f32_16x16x32_bf16 v[112:115], v[172:175], v[198:201], v[112:115]
	v_mfma_f32_16x16x32_bf16 v[112:115], v[180:183], v[202:205], v[112:115]
	v_mfma_f32_16x16x32_bf16 v[104:107], v[184:187], v[198:201], v[104:107]
	v_mfma_f32_16x16x32_bf16 v[104:107], v[194:197], v[202:205], v[104:107]
	v_mfma_f32_16x16x32_bf16 v[96:99], v[172:175], v[206:209], v[96:99]
	v_mfma_f32_16x16x32_bf16 v[96:99], v[180:183], v[210:213], v[96:99]
	v_mfma_f32_16x16x32_bf16 v[88:91], v[184:187], v[206:209], v[88:91]
	v_mfma_f32_16x16x32_bf16 v[88:91], v[194:197], v[210:213], v[88:91]
	v_mfma_f32_16x16x32_bf16 v[80:83], v[172:175], v[214:217], v[80:83]
	v_mfma_f32_16x16x32_bf16 v[80:83], v[180:183], v[218:221], v[80:83]
	v_mfma_f32_16x16x32_bf16 v[72:75], v[184:187], v[214:217], v[72:75]
	v_mfma_f32_16x16x32_bf16 v[72:75], v[194:197], v[218:221], v[72:75]
	v_mfma_f32_16x16x32_bf16 v[68:71], v[172:175], v[222:225], v[68:71]
	v_mfma_f32_16x16x32_bf16 v[68:71], v[180:183], v[226:229], v[68:71]
	v_mfma_f32_16x16x32_bf16 v[64:67], v[184:187], v[222:225], v[64:67]
	v_mfma_f32_16x16x32_bf16 v[64:67], v[194:197], v[226:229], v[64:67]
	s_setprio 0
	s_barrier
; #define PG8_STAGE(bufoff, gbase, voff) do { _Pragma("unroll") for (int _i = 0; _i < 2; ++_i) \
;         __builtin_amdgcn_global_load_lds((const unsigned*)((const char*)(gbase) + (voff)[_i]), (LAS unsigned*)(lds + (bufoff) + ldsw + _i * 8192), 16, 0, 0); } while (0)
; #define PG8_LDA(dst, b, h) do { _Pragma("unroll") for (int m = 0; m < 4; ++m) _Pragma("unroll") for (int k = 0; k < 2; ++k) dst[m][k] = *(const LAS bf16x8*)(lds + PG8_SA(b, h) + aoff + m * 2048 + k * 1024); } while (0)
; #define PG8_MMA(ai, bj, At, Bt) do { __builtin_amdgcn_s_setprio(3); _Pragma("unroll") for (int m = 0; m < 4; ++m) _Pragma("unroll") for (int n = 0; n < 2; ++n) _Pragma("unroll") for (int k = 0; k < 2; ++k) \
;         acc[ai][bj][m][n] = __builtin_amdgcn_mfma_f32_16x16x32_bf16(Bt[n][k], At[m][k], acc[ai][bj][m][n], 0, 0, 0); __builtin_amdgcn_s_setprio(0); } while (0)
; #define PG8_WAIT_V(n) asm volatile("s_waitcnt vmcnt(" #n ")" ::: "memory")
; #define PG8_WAIT_L(n) asm volatile("s_waitcnt lgkmcnt(" #n ")" ::: "memory")
; #define PG8_BAR __builtin_amdgcn_s_barrier()
; #define PG8_SCHED __builtin_amdgcn_sched_barrier(0)
; template <class Epi>
; __device__ __forceinline__ void gemm_phase(LAS unsigned char* lds, const Gemm g, const StaticOrder& S, const Epi& E, const int tid) {
;     ...
;         for (int t = 0; t < nt; t += 2) {
;             const bool last = (t == nt - 2);
;             const char* a1 = cA + (size_t)(t + 1) * kstep;
;             const char* a2 = last ? nA : cA + (size_t)(t + 2) * kstep; const char* b2 = last ? nB : cB + (size_t)(t + 2) * kstep;
;     ...
;             PG8_LDA(At, 1, 1); PG8_STAGE(PG8_SB(1, 0), b3, voffB); PG8_STAGE(PG8_SB(1, 1), b3 + hstepB, voffB); PG8_STAGE(PG8_SA(1, 0), a3, voffA);
;             PG8_WAIT_V(8); PG8_WAIT_L(0); PG8_BAR; PG8_MMA(1, 0, At, B0); PG8_MMA(1, 1, At, B1); PG8_BAR; PG8_SCHED;
	s_add_i32 s6, s21, s93
	v_lshl_add_u64 v[156:157], v[156:157], 0, s[22:23]
	s_mov_b32 m0, s6
	ds_read_b128 v[198:201], v171 offset:49152
	ds_read_b128 v[202:205], v171 offset:50176
	ds_read_b128 v[206:209], v171 offset:51200
	ds_read_b128 v[210:213], v171 offset:52224
	ds_read_b128 v[214:217], v171 offset:53248
	ds_read_b128 v[218:221], v171 offset:54272
	ds_read_b128 v[222:225], v171 offset:55296
	ds_read_b128 v[226:229], v171 offset:56320
	global_load_lds_dwordx4 v[156:157], off
	v_lshl_add_u64 v[156:157], v[190:191], 0, s[22:23]
	s_add_i32 m0, s6, 0x2000
	s_add_i32 s6, s55, s93
	global_load_lds_dwordx4 v[156:157], off
	v_lshl_add_u64 v[156:157], v[240:241], 0, s[22:23]
	s_mov_b32 m0, s6
	s_nop 0
	global_load_lds_dwordx4 v[156:157], off
	v_lshl_add_u64 v[156:157], v[242:243], 0, s[22:23]
	s_add_i32 m0, s6, 0x2000
	s_nop 0
	global_load_lds_dwordx4 v[156:157], off
	v_lshl_add_u64 v[156:157], v[244:245], 0, s[22:23]
	s_mov_b32 m0, s98
	s_nop 0
	global_load_lds_dwordx4 v[156:157], off
	v_lshl_add_u64 v[156:157], v[246:247], 0, s[22:23]
	s_mov_b32 m0, s99
	s_nop 0
	global_load_lds_dwordx4 v[156:157], off
	s_waitcnt vmcnt(8)
	s_waitcnt lgkmcnt(0)
	s_barrier
	s_setprio 3
	s_waitcnt lgkmcnt(0)
	v_mfma_f32_16x16x32_bf16 v[60:63], v[140:143], v[198:201], v[60:63]
	v_mfma_f32_16x16x32_bf16 v[60:63], v[144:147], v[202:205], v[60:63]
	v_mfma_f32_16x16x32_bf16 v[56:59], v[148:151], v[198:201], v[56:59]
	v_mfma_f32_16x16x32_bf16 v[56:59], v[152:155], v[202:205], v[56:59]
	v_mfma_f32_16x16x32_bf16 v[48:51], v[140:143], v[206:209], v[48:51]
	v_mfma_f32_16x16x32_bf16 v[48:51], v[144:147], v[210:213], v[48:51]
	v_mfma_f32_16x16x32_bf16 v[40:43], v[148:151], v[206:209], v[40:43]
	v_mfma_f32_16x16x32_bf16 v[40:43], v[152:155], v[210:213], v[40:43]
	v_mfma_f32_16x16x32_bf16 v[32:35], v[140:143], v[214:217], v[32:35]
	v_mfma_f32_16x16x32_bf16 v[32:35], v[144:147], v[218:221], v[32:35]
	v_mfma_f32_16x16x32_bf16 v[24:27], v[148:151], v[214:217], v[24:27]
	v_mfma_f32_16x16x32_bf16 v[24:27], v[152:155], v[218:221], v[24:27]
	v_mfma_f32_16x16x32_bf16 v[16:19], v[140:143], v[222:225], v[16:19]
	v_mfma_f32_16x16x32_bf16 v[16:19], v[144:147], v[226:229], v[16:19]
	v_mfma_f32_16x16x32_bf16 v[8:11], v[148:151], v[222:225], v[8:11]
	v_mfma_f32_16x16x32_bf16 v[8:11], v[152:155], v[226:229], v[8:11]
	s_setprio 0
	s_setprio 3
	v_mfma_f32_16x16x32_bf16 v[52:55], v[172:175], v[198:201], v[52:55]
	v_mfma_f32_16x16x32_bf16 v[52:55], v[180:183], v[202:205], v[52:55]
	v_mfma_f32_16x16x32_bf16 v[44:47], v[184:187], v[198:201], v[44:47]
	v_mfma_f32_16x16x32_bf16 v[44:47], v[194:197], v[202:205], v[44:47]
	v_mfma_f32_16x16x32_bf16 v[36:39], v[172:175], v[206:209], v[36:39]
	v_mfma_f32_16x16x32_bf16 v[36:39], v[180:183], v[210:213], v[36:39]
	v_mfma_f32_16x16x32_bf16 v[28:31], v[184:187], v[206:209], v[28:31]
	v_mfma_f32_16x16x32_bf16 v[28:31], v[194:197], v[210:213], v[28:31]
	v_mfma_f32_16x16x32_bf16 v[20:23], v[172:175], v[214:217], v[20:23]
	v_mfma_f32_16x16x32_bf16 v[20:23], v[180:183], v[218:221], v[20:23]
	v_mfma_f32_16x16x32_bf16 v[12:15], v[184:187], v[214:217], v[12:15]
	v_mfma_f32_16x16x32_bf16 v[12:15], v[194:197], v[218:221], v[12:15]
	v_mfma_f32_16x16x32_bf16 v[4:7], v[172:175], v[222:225], v[4:7]
	v_mfma_f32_16x16x32_bf16 v[4:7], v[180:183], v[226:229], v[4:7]
	v_mfma_f32_16x16x32_bf16 v[0:3], v[184:187], v[222:225], v[0:3]
	v_mfma_f32_16x16x32_bf16 v[0:3], v[194:197], v[226:229], v[0:3]
	s_setprio 0
	s_barrier
	s_add_u32 s30, s30, 0x100
	s_addc_u32 s31, s31, 0
	s_add_u32 s4, s4, 0x100
	s_addc_u32 s5, s5, 0
	s_cmp_ge_u32 s20, s89
	s_mov_b32 s6, s20
	s_cbranch_scc0 .LBB0_265
